# plus: phase-1 S5 items dealt 3 to the HGRN2 wave and 1 to the retention wave; HGRN2 carry counted wait
# baseline (speedup 1.0000x reference)
; #define LAS __attribute__((address_space(3)))
; __device__ __forceinline__ int vzero() { int z; asm volatile("v_mov_b32 %0, 0" : "=v"(z)); return z; }
; __device__ __forceinline__ void hg_pass1(const Frame& F, int layer, int idx, LAS unsigned char* scr) {
;     const int lane = F.lane + vzero(), r16 = lane & 15, g4 = lane >> 4;
;     const int bh = idx >> 5, sc = idx & 31, b = bh >> 2, h = bh & 3;
;     LAS bf16_t* Kh = (LAS bf16_t*)scr;
;     LAS bf16_t* Vs = (LAS bf16_t*)(scr + 8192);
;     const bf16_t* H = WSP(const bf16_t, WS_H);
;     const float lbv = ((const float*)(F.ws + WS_S5P + S5P_LB))[layer * 256 + h * 64 + lane], oml = 1.0f - lbv;
;     const size_t t0 = (size_t)b * SEQ + sc * 64;
;     float P = 1.0f;
; #pragma unroll 1
;     ...
;         bf16_t fx[16], ix[16];
; #pragma unroll
;         for (int j = 0; j < 16; ++j) { const bf16_t* row = H + (t0 + tb * 16 + j) * HP + h * 64 + lane; fx[j] = row[C_HF]; ix[j] = row[C_HI]; }
; __global__ void __launch_bounds__(512, 2) hybrid_fwd(Args args) {
;     ...
;             if (F.NGW == 2048) {
;                 if (F.gw < 1024) { if (!(VAR & 2)) hg_pass1(F, L, F.gw, wscr);
;                     if (!(VAR & 8)) { for (int j = 0; j < 4; ++j) s5_item<false>(F, L, F.gw * 4 + j, wscr); } }
;                 else { if (!(VAR & 4)) ret_item1(F, F.gw - 1024, wscr); }
.LBB0_942:
	s_add_i32 s6, s6, 0xfffffc00
	s_mov_b32 s101, 4
	s_branch .LBB0_948
.LBB0_943:
	s_andn2_b64 vcc, exec, s[0:1]
	s_cbranch_vccnz .LBB0_973
	s_mov_b32 s101, 3
	v_readlane_b32 s0, v254, 11
	v_readlane_b32 s1, v254, 12
	s_andn2_b64 vcc, exec, s[0:1]
	s_cbranch_vccnz .LBB0_948
	s_lshl_b32 s1, s6, 1
	s_lshl_b32 s0, s14, 8
	s_and_b32 s1, s1, 0xc0
	v_mov_b32 v2, 0
	s_or_b32 s0, s1, s0
	v_add_u32_e32 v40, v2, v54
	v_add_u32_e32 v2, s0, v40
	v_ashrrev_i32_e32 v3, 31, v2
	v_lshl_add_u64 v[2:3], v[2:3], 2, s[10:11]
	v_add_co_u32_e32 v2, vcc, 0x1d4b0000, v2
	s_mul_i32 s1, s8, 0x4001
	s_nop 0
	v_addc_co_u32_e32 v3, vcc, 0, v3, vcc
	global_load_dword v2, v[2:3], off
	s_mul_i32 s4, s8, 9
	v_readlane_b32 s5, v254, 49
	v_readlane_b32 s7, v254, 50
	s_add_i32 s1, s5, s1
	s_add_i32 s4, s7, s4
	s_ashr_i32 s0, s6, 7
	v_lshl_add_u32 v16, v40, 1, s1
	s_and_b32 s1, s4, 31
	s_mul_hi_i32 s5, s0, 0xb00000
	s_mul_i32 s0, s0, 0xb00000
	s_mul_i32 s1, s1, 0x58000
	s_add_u32 s0, s0, s1
	s_addc_u32 s1, s5, 0
	s_lshl_b32 s4, s6, 2
	s_and_b32 s4, s4, 0x180
	s_or_b32 s0, s0, s4
	v_readlane_b32 s4, v254, 52
	s_add_u32 s4, s4, s8
	v_readlane_b32 s5, v254, 53
	s_addc_u32 s5, s5, s9
	s_add_u32 s0, s4, s0
	v_ashrrev_i32_e32 v41, 31, v40
	s_addc_u32 s1, s5, s1
	s_mov_b32 s16, 0xfffea000
	v_mov_b32_e32 v43, 1.0
	v_lshl_add_u64 v[4:5], v[40:41], 1, s[0:1]
	s_movk_i32 s0, 0x1800
	s_mov_b32 s1, 0x10000
	s_mov_b32 s4, 0x11000
	s_mov_b32 s5, 0x12000
	s_mov_b32 s7, 0x13000
	s_mov_b32 s17, -1
	s_waitcnt vmcnt(0)
	v_sub_f32_e32 v42, 1.0, v2

; #define LAS __attribute__((address_space(3)))
; __device__ __forceinline__ int vzero() { int z; asm volatile("v_mov_b32 %0, 0" : "=v"(z)); return z; }
; template <bool OUT>
; __device__ __forceinline__ void s5_item(const Frame& F, int layer, int idx, LAS unsigned char* scr) {
;     const int lane = F.lane + vzero(), r16 = lane & 15, g4 = lane >> 4;
;     const int bg = idx >> 5, n = idx & 31, b = bg >> 4, g = bg & 15;
;     LAS float* bu = (LAS float*)scr;
;     LAS bf16_t* xs = (LAS bf16_t*)(scr + 8448);
;     const float* abar = (const float*)(F.ws + WS_S5P + S5P_ABAR) + ((size_t)(layer * 16 + g) * 64 + lane) * 2;
;     const float ar = abar[0], ai = abar[1];
;     const bf16_t* Bm = (const bf16_t*)(F.ws + WS_S5P + S5P_BM) + (size_t)(layer * 16 + g) * 128 * 16;
;     const bf16_t* Cm = (const bf16_t*)(F.ws + WS_S5P + S5P_CM) + (size_t)(layer * 16 + g) * 16 * 128;
;     const bf16_t* H = WSP(const bf16_t, WS_H);
;     Frag zf; zf.q = (u32x4){0u, 0u, 0u, 0u};
;     bf16x8 bfr[8];
; #pragma unroll
;     for (int nb = 0; nb < 8; ++nb) bfr[nb] = (g4 < 2) ? *(const bf16x8*)(Bm + (nb * 16 + r16) * 16 + 8 * g4) : zf.v;
;     bf16x8 cfr[4];
;     if (OUT) {
; #pragma unroll
;         for (int ks = 0; ks < 4; ++ks) cfr[ks] = *(const bf16x8*)(Cm + r16 * 128 + 32 * ks + 8 * g4); }
;     float xr = 0.f, xi = 0.f;
;     if (OUT && n > 0) { const float* ci = WSP(const float, WS_S5C) + ((size_t)(bg * 32 + n) * 64 + lane) * 2; xr = ci[0]; xi = ci[1]; }
;     const float dsk = OUT ? IN_F(11)[layer * 256 + g * 16 + r16] : 0.f;
;     const size_t tok0 = (size_t)b * SEQ + n * 64;
; __global__ void __launch_bounds__(512, 2) hybrid_fwd(Args args) {
;     ...
;                 if (F.gw < 1024) { if (!(VAR & 2)) hg_pass1(F, L, F.gw, wscr);
;                     if (!(VAR & 8)) { for (int j = 0; j < 4; ++j) s5_item<false>(F, L, F.gw * 4 + j, wscr); } }
;                 else { if (!(VAR & 4)) ret_item1(F, F.gw - 1024, wscr); }
.LBB0_948:
	s_andn2_b64 vcc, exec, s[90:91]
	s_cbranch_vccnz .LBB0_973
	s_bfe_u32 s16, s6, 0x40003
	s_lshl_b32 s0, s14, 4
	s_or_b32 s0, s16, s0
	s_ashr_i32 s1, s0, 31
	s_lshl_b32 s18, s6, 2
	s_lshl_b64 s[4:5], s[0:1], 9
	s_add_u32 s4, s10, s4
	s_addc_u32 s5, s11, s5
	s_add_u32 s4, s4, 0x1d400000
	s_addc_u32 s5, s5, 0
	s_lshl_b64 s[0:1], s[0:1], 12
	s_add_u32 s0, s10, s0
	s_addc_u32 s1, s11, s1
	s_add_u32 s14, s0, 0x1d410000
	s_addc_u32 s15, s1, 0
	s_ashr_i32 s0, s6, 7
	s_ashr_i32 s1, s0, 31
	s_lshl_b64 s[6:7], s[0:1], 11
	s_lshl_b32 s1, s16, 5
	s_add_u32 s12, s12, s1
	s_addc_u32 s13, s13, 0
	s_add_u32 s19, s10, 0x3a600000
	s_mul_hi_i32 s10, s0, 0xb00000
	s_mul_i32 s0, s0, 0xb00000
	s_addc_u32 s20, s11, 0
	s_or_b32 s0, s0, s1
	s_add_u32 s0, s0, s8
	s_addc_u32 s1, s10, s9
	v_readlane_b32 s8, v254, 44
	s_add_u32 s8, s8, s0
	v_readlane_b32 s0, v254, 46
	s_addc_u32 s9, s0, s1
	s_sub_i32 s21, s101, 3
	s_mul_i32 s21, s21, 3
	s_add_i32 s22, s18, s21
	s_branch .LBB0_951
.LBB0_950:
	s_ashr_i32 s11, s10, 31
	s_lshl_b64 s[0:1], s[10:11], 9
	s_add_u32 s0, s19, s0
	s_addc_u32 s1, s20, s1
	s_add_i32 s21, s21, 1
	s_add_i32 s22, s22, 1
	v_lshl_add_u64 v[2:3], s[0:1], 0, v[44:45]
	s_cmp_eq_u32 s21, s101
	global_store_dwordx2 v[2:3], v[52:53], off
	s_cbranch_scc1 .LBB0_973

; __device__ __forceinline__ void hg_carry(const Frame& F) {
;     if (F.tid >= 256) return;
;     const int gt = F.bid * 256 + F.tid; if (gt >= 32 * 2048) return;
;     const int bh = gt >> 11, kv2 = gt & 2047, k = kv2 >> 5;
;     const unsigned* E = WSP(const unsigned, WS_HGE); const float* Dt = WSP(const float, WS_HGD); unsigned* I = WSP(unsigned, WS_HGI);
;     unsigned e[32]; float d[32];
; #pragma unroll
;     for (int sc = 0; sc < 32; ++sc) { e[sc] = E[(size_t)(bh * 32 + sc) * 2048 + kv2]; d[sc] = Dt[(size_t)(bh * 32 + sc) * 64 + k]; }
.LBB0_1028:
	s_or_b64 exec, exec, s[4:5]
	s_movk_i32 s4, 0x100
	v_cmp_gt_i32_e32 vcc, s4, v109
	v_lshl_add_u32 v63, s26, 8, v109
	s_and_saveexec_b64 s[4:5], vcc
	s_cbranch_execz .LBB0_1031
	s_mov_b32 s8, 0x10000
	v_cmp_gt_i32_e32 vcc, s8, v63
	s_and_b64 exec, exec, vcc
	s_cbranch_execz .LBB0_1031
	v_and_b32_e32 v2, 0x7ff, v63
	v_ashrrev_i32_e32 v73, 6, v63
	v_lshlrev_b32_e32 v34, 2, v2
	v_lshrrev_b32_e32 v4, 3, v63
	v_and_b32_e32 v64, 0xffffffe0, v73
	v_lshl_add_u64 v[2:3], s[0:1], 0, v[34:35]
	s_mov_b64 s[8:9], 0x3ab00000
	v_and_b32_e32 v34, 0xfc, v4
	v_lshl_add_u64 v[66:67], v[2:3], 0, s[8:9]
	v_lshl_add_u64 v[4:5], s[0:1], 0, v[34:35]
	s_mov_b64 s[8:9], 0x3aa00000
	v_ashrrev_i32_e32 v65, 31, v64
	v_lshl_add_u64 v[68:69], v[4:5], 0, s[8:9]
	v_lshlrev_b64 v[4:5], 13, v[64:65]
	v_or_b32_e32 v6, 1, v64
	v_lshl_add_u64 v[4:5], v[66:67], 0, v[4:5]
	v_ashrrev_i32_e32 v7, 31, v6
	global_load_dword v71, v[4:5], off
	v_lshlrev_b64 v[4:5], 13, v[6:7]
	v_lshlrev_b64 v[6:7], 8, v[6:7]
	v_lshl_add_u64 v[8:9], v[66:67], 0, v[4:5]
	v_lshl_add_u64 v[6:7], v[68:69], 0, v[6:7]
	global_load_dword v77, v[8:9], off
	global_load_dword v62, v[6:7], off
	v_or_b32_e32 v8, 2, v64
	v_ashrrev_i32_e32 v9, 31, v8
	v_lshlrev_b64 v[6:7], 13, v[8:9]
	v_lshlrev_b64 v[8:9], 8, v[8:9]
	v_lshl_add_u64 v[10:11], v[66:67], 0, v[6:7]
	v_lshl_add_u64 v[8:9], v[68:69], 0, v[8:9]
	global_load_dword v79, v[10:11], off
	global_load_dword v72, v[8:9], off
	v_or_b32_e32 v10, 3, v64
	v_ashrrev_i32_e32 v11, 31, v10
	v_lshlrev_b64 v[8:9], 13, v[10:11]
	v_lshlrev_b64 v[10:11], 8, v[10:11]
	v_lshl_add_u64 v[12:13], v[66:67], 0, v[8:9]
	v_lshl_add_u64 v[10:11], v[68:69], 0, v[10:11]
	global_load_dword v81, v[12:13], off
	global_load_dword v34, v[10:11], off
	v_or_b32_e32 v12, 4, v64
	v_ashrrev_i32_e32 v13, 31, v12
	v_lshlrev_b64 v[10:11], 13, v[12:13]
	v_lshlrev_b64 v[12:13], 8, v[12:13]
	v_lshl_add_u64 v[14:15], v[66:67], 0, v[10:11]
	v_lshl_add_u64 v[12:13], v[68:69], 0, v[12:13]
	global_load_dword v87, v[14:15], off
	global_load_dword v78, v[12:13], off
	v_or_b32_e32 v14, 5, v64
	v_ashrrev_i32_e32 v15, 31, v14
	v_lshlrev_b64 v[12:13], 13, v[14:15]
	v_lshlrev_b64 v[14:15], 8, v[14:15]
	v_lshl_add_u64 v[16:17], v[66:67], 0, v[12:13]
	v_lshl_add_u64 v[14:15], v[68:69], 0, v[14:15]
	global_load_dword v85, v[16:17], off
	global_load_dword v70, v[14:15], off
	v_or_b32_e32 v16, 6, v64
	v_ashrrev_i32_e32 v17, 31, v16
	v_lshlrev_b64 v[14:15], 13, v[16:17]
	v_lshlrev_b64 v[16:17], 8, v[16:17]
	v_lshl_add_u64 v[18:19], v[66:67], 0, v[14:15]
	v_lshl_add_u64 v[16:17], v[68:69], 0, v[16:17]
	global_load_dword v83, v[18:19], off
	global_load_dword v76, v[16:17], off
	v_or_b32_e32 v18, 7, v64
	v_ashrrev_i32_e32 v19, 31, v18
	v_lshlrev_b64 v[16:17], 13, v[18:19]
	v_lshlrev_b64 v[18:19], 8, v[18:19]
	v_lshl_add_u64 v[20:21], v[66:67], 0, v[16:17]
	v_lshl_add_u64 v[18:19], v[68:69], 0, v[18:19]
	global_load_dword v89, v[20:21], off
	global_load_dword v82, v[18:19], off
	v_or_b32_e32 v20, 8, v64
	v_ashrrev_i32_e32 v21, 31, v20
	v_lshlrev_b64 v[18:19], 13, v[20:21]
	v_lshlrev_b64 v[20:21], 8, v[20:21]
	v_lshl_add_u64 v[22:23], v[66:67], 0, v[18:19]
	v_lshl_add_u64 v[20:21], v[68:69], 0, v[20:21]
	global_load_dword v97, v[22:23], off
	global_load_dword v84, v[20:21], off
	v_or_b32_e32 v22, 9, v64
	v_ashrrev_i32_e32 v23, 31, v22
	v_lshlrev_b64 v[20:21], 13, v[22:23]
	v_lshlrev_b64 v[22:23], 8, v[22:23]
	v_lshl_add_u64 v[24:25], v[66:67], 0, v[20:21]
	v_lshl_add_u64 v[22:23], v[68:69], 0, v[22:23]
	global_load_dword v93, v[24:25], off
	global_load_dword v88, v[22:23], off
	v_or_b32_e32 v24, 10, v64
	v_ashrrev_i32_e32 v25, 31, v24
	v_lshlrev_b64 v[22:23], 13, v[24:25]
	v_lshlrev_b64 v[24:25], 8, v[24:25]
	v_lshl_add_u64 v[26:27], v[66:67], 0, v[22:23]
	v_lshl_add_u64 v[24:25], v[68:69], 0, v[24:25]
	global_load_dword v95, v[26:27], off
	global_load_dword v80, v[24:25], off
	v_or_b32_e32 v26, 11, v64
	v_ashrrev_i32_e32 v27, 31, v26
	v_lshlrev_b64 v[24:25], 13, v[26:27]
	v_lshlrev_b64 v[26:27], 8, v[26:27]
	v_lshl_add_u64 v[28:29], v[66:67], 0, v[24:25]
	v_lshl_add_u64 v[26:27], v[68:69], 0, v[26:27]
	global_load_dword v91, v[28:29], off
	global_load_dword v86, v[26:27], off
	v_or_b32_e32 v28, 12, v64
	v_ashrrev_i32_e32 v29, 31, v28
	v_lshlrev_b64 v[26:27], 13, v[28:29]
	v_lshlrev_b64 v[28:29], 8, v[28:29]
	v_lshl_add_u64 v[30:31], v[66:67], 0, v[26:27]
	v_lshl_add_u64 v[28:29], v[68:69], 0, v[28:29]
	global_load_dword v105, v[30:31], off
	global_load_dword v96, v[28:29], off
	v_or_b32_e32 v30, 13, v64
	v_ashrrev_i32_e32 v31, 31, v30
	v_lshlrev_b64 v[28:29], 13, v[30:31]
	v_lshlrev_b64 v[30:31], 8, v[30:31]
	v_lshl_add_u64 v[32:33], v[66:67], 0, v[28:29]
	v_lshl_add_u64 v[30:31], v[68:69], 0, v[30:31]
	global_load_dword v103, v[32:33], off
	global_load_dword v92, v[30:31], off
	v_or_b32_e32 v32, 14, v64
	v_ashrrev_i32_e32 v33, 31, v32
	v_lshlrev_b64 v[30:31], 13, v[32:33]
	v_lshlrev_b64 v[32:33], 8, v[32:33]
	v_lshl_add_u64 v[36:37], v[66:67], 0, v[30:31]
	v_lshl_add_u64 v[32:33], v[68:69], 0, v[32:33]
	global_load_dword v99, v[36:37], off
	global_load_dword v94, v[32:33], off
	v_or_b32_e32 v36, 15, v64
	v_ashrrev_i32_e32 v37, 31, v36
	v_lshlrev_b64 v[32:33], 13, v[36:37]
	v_lshlrev_b64 v[36:37], 8, v[36:37]
	v_lshl_add_u64 v[38:39], v[66:67], 0, v[32:33]
	v_lshl_add_u64 v[36:37], v[68:69], 0, v[36:37]
	global_load_dword v101, v[38:39], off
	global_load_dword v90, v[36:37], off
	v_or_b32_e32 v38, 16, v64
	v_ashrrev_i32_e32 v39, 31, v38
	v_lshlrev_b64 v[36:37], 13, v[38:39]
	v_lshlrev_b64 v[38:39], 8, v[38:39]
	v_lshl_add_u64 v[40:41], v[66:67], 0, v[36:37]
	v_lshl_add_u64 v[38:39], v[68:69], 0, v[38:39]
; __device__ __forceinline__ void hg_carry(const Frame& F) {
;     if (F.tid >= 256) return;
;     const int gt = F.bid * 256 + F.tid; if (gt >= 32 * 2048) return;
;     const int bh = gt >> 11, kv2 = gt & 2047, k = kv2 >> 5;
;     const unsigned* E = WSP(const unsigned, WS_HGE); const float* Dt = WSP(const float, WS_HGD); unsigned* I = WSP(unsigned, WS_HGI);
;     unsigned e[32]; float d[32];
; #pragma unroll
;     for (int sc = 0; sc < 32; ++sc) { e[sc] = E[(size_t)(bh * 32 + sc) * 2048 + kv2]; d[sc] = Dt[(size_t)(bh * 32 + sc) * 64 + k]; }
	global_load_dword v111, v[40:41], off
	global_load_dword v100, v[38:39], off
	v_or_b32_e32 v40, 17, v64
	v_ashrrev_i32_e32 v41, 31, v40
	v_lshlrev_b64 v[38:39], 13, v[40:41]
	v_lshlrev_b64 v[40:41], 8, v[40:41]
	v_lshl_add_u64 v[42:43], v[66:67], 0, v[38:39]
	v_lshl_add_u64 v[40:41], v[68:69], 0, v[40:41]
	global_load_dword v113, v[42:43], off
	global_load_dword v106, v[40:41], off
	v_or_b32_e32 v42, 18, v64
	v_ashrrev_i32_e32 v43, 31, v42
	v_lshlrev_b64 v[40:41], 13, v[42:43]
	v_lshlrev_b64 v[42:43], 8, v[42:43]
	v_lshl_add_u64 v[44:45], v[66:67], 0, v[40:41]
	v_lshl_add_u64 v[42:43], v[68:69], 0, v[42:43]
	global_load_dword v115, v[44:45], off
	global_load_dword v98, v[42:43], off
	v_or_b32_e32 v44, 19, v64
	v_ashrrev_i32_e32 v45, 31, v44
	v_lshlrev_b64 v[42:43], 13, v[44:45]
	v_lshlrev_b64 v[44:45], 8, v[44:45]
	v_lshl_add_u64 v[46:47], v[66:67], 0, v[42:43]
	v_lshl_add_u64 v[44:45], v[68:69], 0, v[44:45]
	global_load_dword v107, v[46:47], off
	global_load_dword v102, v[44:45], off
	v_or_b32_e32 v46, 20, v64
	v_ashrrev_i32_e32 v47, 31, v46
	v_lshlrev_b64 v[44:45], 13, v[46:47]
	v_lshlrev_b64 v[46:47], 8, v[46:47]
	v_lshl_add_u64 v[48:49], v[66:67], 0, v[44:45]
	v_lshl_add_u64 v[46:47], v[68:69], 0, v[46:47]
	global_load_dword v121, v[48:49], off
	global_load_dword v104, v[46:47], off
	v_or_b32_e32 v48, 21, v64
	v_ashrrev_i32_e32 v49, 31, v48
	v_lshlrev_b64 v[46:47], 13, v[48:49]
	v_lshlrev_b64 v[48:49], 8, v[48:49]
	v_lshl_add_u64 v[50:51], v[66:67], 0, v[46:47]
	v_lshl_add_u64 v[48:49], v[68:69], 0, v[48:49]
	global_load_dword v117, v[50:51], off
	global_load_dword v110, v[48:49], off
	v_or_b32_e32 v50, 22, v64
	v_ashrrev_i32_e32 v51, 31, v50
	v_lshlrev_b64 v[48:49], 13, v[50:51]
	v_lshlrev_b64 v[50:51], 8, v[50:51]
	v_lshl_add_u64 v[52:53], v[66:67], 0, v[48:49]
	v_lshl_add_u64 v[50:51], v[68:69], 0, v[50:51]
	global_load_dword v119, v[52:53], off
	global_load_dword v114, v[50:51], off
	v_or_b32_e32 v52, 23, v64
	v_ashrrev_i32_e32 v53, 31, v52
	v_lshlrev_b64 v[50:51], 13, v[52:53]
	v_lshlrev_b64 v[52:53], 8, v[52:53]
	v_lshl_add_u64 v[54:55], v[66:67], 0, v[50:51]
	v_lshl_add_u64 v[52:53], v[68:69], 0, v[52:53]
	global_load_dword v123, v[54:55], off
	global_load_dword v108, v[52:53], off
	v_or_b32_e32 v54, 24, v64
	v_ashrrev_i32_e32 v55, 31, v54
	v_lshlrev_b64 v[52:53], 13, v[54:55]
	v_lshlrev_b64 v[54:55], 8, v[54:55]
	v_lshl_add_u64 v[56:57], v[66:67], 0, v[52:53]
	v_lshl_add_u64 v[54:55], v[68:69], 0, v[54:55]
	global_load_dword v127, v[56:57], off
	global_load_dword v118, v[54:55], off
	v_or_b32_e32 v56, 25, v64
	v_ashrrev_i32_e32 v57, 31, v56
	v_lshlrev_b64 v[54:55], 13, v[56:57]
	v_lshlrev_b64 v[56:57], 8, v[56:57]
	v_lshl_add_u64 v[58:59], v[66:67], 0, v[54:55]
	v_lshl_add_u64 v[56:57], v[68:69], 0, v[56:57]
	global_load_dword v126, v[58:59], off
	global_load_dword v112, v[56:57], off
	v_or_b32_e32 v58, 26, v64
	v_ashrrev_i32_e32 v59, 31, v58
	v_lshlrev_b64 v[56:57], 13, v[58:59]
	v_lshlrev_b64 v[58:59], 8, v[58:59]
	v_lshl_add_u64 v[60:61], v[66:67], 0, v[56:57]
	v_lshl_add_u64 v[58:59], v[68:69], 0, v[58:59]
	global_load_dword v125, v[60:61], off
	global_load_dword v116, v[58:59], off
	v_or_b32_e32 v60, 27, v64
	v_ashrrev_i32_e32 v61, 31, v60
	v_lshlrev_b64 v[58:59], 13, v[60:61]
	v_lshlrev_b64 v[60:61], 8, v[60:61]
	v_lshl_add_u64 v[74:75], v[66:67], 0, v[58:59]
	v_lshl_add_u64 v[60:61], v[68:69], 0, v[60:61]
	global_load_dword v128, v[74:75], off
	global_load_dword v120, v[60:61], off
	v_or_b32_e32 v74, 28, v64
	v_ashrrev_i32_e32 v75, 31, v74
	v_lshlrev_b64 v[60:61], 13, v[74:75]
	v_lshlrev_b64 v[74:75], 8, v[74:75]
	v_lshl_add_u64 v[130:131], v[66:67], 0, v[60:61]
	v_lshl_add_u64 v[74:75], v[68:69], 0, v[74:75]
	global_load_dword v134, v[130:131], off
	global_load_dword v122, v[74:75], off
	v_or_b32_e32 v130, 29, v64
	v_ashrrev_i32_e32 v131, 31, v130
	v_lshlrev_b64 v[74:75], 13, v[130:131]
	v_lshlrev_b64 v[130:131], 8, v[130:131]
	v_lshl_add_u64 v[130:131], v[68:69], 0, v[130:131]
	global_load_dword v124, v[130:131], off
	v_or_b32_e32 v130, 30, v64
	v_ashrrev_i32_e32 v131, 31, v130
	v_lshlrev_b64 v[64:65], 13, v[130:131]
	v_lshl_add_u64 v[132:133], v[66:67], 0, v[74:75]
	v_lshl_add_u64 v[66:67], v[66:67], 0, v[64:65]
	global_load_dword v129, v[132:133], off
	global_load_dword v135, v[66:67], off
	v_lshlrev_b64 v[66:67], 8, v[130:131]
	s_waitcnt vmcnt(0)
; __device__ __forceinline__ float h2f_(unsigned short b) { return (float)__builtin_bit_cast(_Float16, b); }
; __device__ __forceinline__ void hg_carry(const Frame& F) {
;     ...
;     float s0 = h2f_((unsigned short)(e[0] & 0xffffu)), s1 = h2f_((unsigned short)(e[0] >> 16));
; #pragma unroll
;     for (int sc = 1; sc < 32; ++sc) { const float n0 = d[sc] * s0 + h2f_((unsigned short)(e[sc] & 0xffffu)), n1 = d[sc] * s1 + h2f_((unsigned short)(e[sc] >> 16)); e[sc] = cvt_pk_f16(s0, s1); s0 = n0; s1 = n1; }
; #pragma unroll
;     for (int sc = 1; sc < 32; ++sc) I[(size_t)(bh * 32 + sc) * 2048 + kv2] = e[sc];
	v_cvt_f32_f16_e32 v130, v71
	v_cvt_f32_f16_sdwa v131, v71 dst_sel:DWORD dst_unused:UNUSED_PAD src0_sel:WORD_1
	v_cvt_f32_f16_e32 v132, v77
	v_cvt_f32_f16_sdwa v133, v77 dst_sel:DWORD dst_unused:UNUSED_PAD src0_sel:WORD_1
	v_lshl_add_u64 v[66:67], v[68:69], 0, v[66:67]
	global_load_dword v68, v[66:67], off
	v_or_b32_e32 v66, 31, v73
	v_pk_fma_f32 v[130:131], v[62:63], v[130:131], v[132:133] op_sel_hi:[0,1,1]
	v_cvt_f32_f16_e32 v132, v79
	v_cvt_f32_f16_sdwa v133, v79 dst_sel:DWORD dst_unused:UNUSED_PAD src0_sel:WORD_1
	v_cvt_pk_f16_f32 v62, v130, v131
	s_mov_b64 s[8:9], 0x3bb00000
	v_lshl_add_u64 v[2:3], v[2:3], 0, s[8:9]
	v_pk_fma_f32 v[72:73], v[72:73], v[130:131], v[132:133] op_sel_hi:[0,1,1]
	v_cvt_f32_f16_e32 v130, v81
	v_cvt_f32_f16_sdwa v131, v81 dst_sel:DWORD dst_unused:UNUSED_PAD src0_sel:WORD_1
	v_lshl_add_u64 v[4:5], v[2:3], 0, v[4:5]
	global_store_dword v[4:5], v71, off
	v_lshl_add_u64 v[4:5], v[2:3], 0, v[6:7]
	v_pk_fma_f32 v[130:131], v[34:35], v[72:73], v[130:131] op_sel_hi:[0,1,1]
	v_cvt_pk_f16_f32 v34, v72, v73
	v_cvt_f32_f16_e32 v72, v87
	v_cvt_f32_f16_sdwa v73, v87 dst_sel:DWORD dst_unused:UNUSED_PAD src0_sel:WORD_1
	v_cvt_pk_f16_f32 v81, v130, v131
	global_store_dword v[4:5], v62, off
	v_lshl_add_u64 v[4:5], v[2:3], 0, v[8:9]
	v_pk_fma_f32 v[72:73], v[78:79], v[130:131], v[72:73] op_sel_hi:[0,1,1]
	v_cvt_f32_f16_e32 v78, v85
	v_cvt_f32_f16_sdwa v79, v85 dst_sel:DWORD dst_unused:UNUSED_PAD src0_sel:WORD_1
	global_store_dword v[4:5], v34, off
	v_lshl_add_u64 v[4:5], v[2:3], 0, v[10:11]
	global_store_dword v[4:5], v81, off
	v_pk_fma_f32 v[78:79], v[70:71], v[72:73], v[78:79] op_sel_hi:[0,1,1]
	v_cvt_pk_f16_f32 v70, v72, v73
	v_cvt_f32_f16_e32 v72, v83
	v_cvt_f32_f16_sdwa v73, v83 dst_sel:DWORD dst_unused:UNUSED_PAD src0_sel:WORD_1
	v_cvt_pk_f16_f32 v85, v78, v79
	v_lshl_add_u64 v[4:5], v[2:3], 0, v[12:13]
	global_store_dword v[4:5], v70, off
	v_pk_fma_f32 v[72:73], v[76:77], v[78:79], v[72:73] op_sel_hi:[0,1,1]
	v_cvt_f32_f16_e32 v76, v89
	v_cvt_f32_f16_sdwa v77, v89 dst_sel:DWORD dst_unused:UNUSED_PAD src0_sel:WORD_1
	v_cvt_pk_f16_f32 v78, v72, v73
	v_lshl_add_u64 v[4:5], v[2:3], 0, v[14:15]
	global_store_dword v[4:5], v85, off
	v_pk_fma_f32 v[76:77], v[82:83], v[72:73], v[76:77] op_sel_hi:[0,1,1]
	v_cvt_f32_f16_e32 v72, v97
	v_cvt_f32_f16_sdwa v73, v97 dst_sel:DWORD dst_unused:UNUSED_PAD src0_sel:WORD_1
	v_cvt_pk_f16_f32 v79, v76, v77
	v_lshl_add_u64 v[4:5], v[2:3], 0, v[16:17]
	global_store_dword v[4:5], v78, off
	v_pk_fma_f32 v[72:73], v[84:85], v[76:77], v[72:73] op_sel_hi:[0,1,1]
	v_cvt_f32_f16_e32 v76, v93
	v_cvt_f32_f16_sdwa v77, v93 dst_sel:DWORD dst_unused:UNUSED_PAD src0_sel:WORD_1
	v_cvt_pk_f16_f32 v82, v72, v73
	v_lshl_add_u64 v[4:5], v[2:3], 0, v[18:19]
	global_store_dword v[4:5], v79, off
	v_pk_fma_f32 v[76:77], v[88:89], v[72:73], v[76:77] op_sel_hi:[0,1,1]
	v_cvt_f32_f16_e32 v72, v95
	v_cvt_f32_f16_sdwa v73, v95 dst_sel:DWORD dst_unused:UNUSED_PAD src0_sel:WORD_1
	v_lshl_add_u64 v[4:5], v[2:3], 0, v[20:21]
	global_store_dword v[4:5], v82, off
	v_lshl_add_u64 v[4:5], v[2:3], 0, v[22:23]
	v_pk_fma_f32 v[72:73], v[80:81], v[76:77], v[72:73] op_sel_hi:[0,1,1]
	v_cvt_pk_f16_f32 v80, v76, v77
	v_cvt_f32_f16_e32 v76, v91
	v_cvt_f32_f16_sdwa v77, v91 dst_sel:DWORD dst_unused:UNUSED_PAD src0_sel:WORD_1
	v_cvt_pk_f16_f32 v83, v72, v73
	global_store_dword v[4:5], v80, off
	v_lshl_add_u64 v[4:5], v[2:3], 0, v[24:25]
	v_pk_fma_f32 v[72:73], v[86:87], v[72:73], v[76:77] op_sel_hi:[0,1,1]
	v_cvt_f32_f16_e32 v76, v105
	v_cvt_f32_f16_sdwa v77, v105 dst_sel:DWORD dst_unused:UNUSED_PAD src0_sel:WORD_1
	v_cvt_pk_f16_f32 v84, v72, v73
	global_store_dword v[4:5], v83, off
	v_lshl_add_u64 v[4:5], v[2:3], 0, v[26:27]
	v_pk_fma_f32 v[76:77], v[96:97], v[72:73], v[76:77] op_sel_hi:[0,1,1]
	v_cvt_f32_f16_e32 v72, v103
	v_cvt_f32_f16_sdwa v73, v103 dst_sel:DWORD dst_unused:UNUSED_PAD src0_sel:WORD_1
	v_cvt_pk_f16_f32 v86, v76, v77
	global_store_dword v[4:5], v84, off
	v_lshl_add_u64 v[4:5], v[2:3], 0, v[28:29]
	v_pk_fma_f32 v[72:73], v[92:93], v[76:77], v[72:73] op_sel_hi:[0,1,1]
	v_cvt_f32_f16_e32 v76, v99
	v_cvt_f32_f16_sdwa v77, v99 dst_sel:DWORD dst_unused:UNUSED_PAD src0_sel:WORD_1
	v_cvt_pk_f16_f32 v87, v72, v73
	global_store_dword v[4:5], v86, off
	v_lshl_add_u64 v[4:5], v[2:3], 0, v[30:31]
	v_pk_fma_f32 v[76:77], v[94:95], v[72:73], v[76:77] op_sel_hi:[0,1,1]
	v_cvt_f32_f16_e32 v72, v101
	v_cvt_f32_f16_sdwa v73, v101 dst_sel:DWORD dst_unused:UNUSED_PAD src0_sel:WORD_1
	v_cvt_pk_f16_f32 v88, v76, v77
	global_store_dword v[4:5], v87, off
	v_lshl_add_u64 v[4:5], v[2:3], 0, v[32:33]
	v_pk_fma_f32 v[72:73], v[90:91], v[76:77], v[72:73] op_sel_hi:[0,1,1]
	v_cvt_f32_f16_e32 v76, v111
; __device__ __forceinline__ float h2f_(unsigned short b) { return (float)__builtin_bit_cast(_Float16, b); }
; __device__ __forceinline__ void hg_carry(const Frame& F) {
;     ...
;     float s0 = h2f_((unsigned short)(e[0] & 0xffffu)), s1 = h2f_((unsigned short)(e[0] >> 16));
; #pragma unroll
;     for (int sc = 1; sc < 32; ++sc) { const float n0 = d[sc] * s0 + h2f_((unsigned short)(e[sc] & 0xffffu)), n1 = d[sc] * s1 + h2f_((unsigned short)(e[sc] >> 16)); e[sc] = cvt_pk_f16(s0, s1); s0 = n0; s1 = n1; }
; #pragma unroll
;     for (int sc = 1; sc < 32; ++sc) I[(size_t)(bh * 32 + sc) * 2048 + kv2] = e[sc];
	v_cvt_f32_f16_sdwa v77, v111 dst_sel:DWORD dst_unused:UNUSED_PAD src0_sel:WORD_1
	v_cvt_pk_f16_f32 v89, v72, v73
	global_store_dword v[4:5], v88, off
	v_lshl_add_u64 v[4:5], v[2:3], 0, v[36:37]
	v_pk_fma_f32 v[72:73], v[100:101], v[72:73], v[76:77] op_sel_hi:[0,1,1]
	v_cvt_f32_f16_e32 v76, v113
	v_cvt_f32_f16_sdwa v77, v113 dst_sel:DWORD dst_unused:UNUSED_PAD src0_sel:WORD_1
	v_cvt_pk_f16_f32 v90, v72, v73
	global_store_dword v[4:5], v89, off
	v_lshl_add_u64 v[4:5], v[2:3], 0, v[38:39]
	v_pk_fma_f32 v[76:77], v[106:107], v[72:73], v[76:77] op_sel_hi:[0,1,1]
	v_cvt_f32_f16_e32 v72, v115
	v_cvt_f32_f16_sdwa v73, v115 dst_sel:DWORD dst_unused:UNUSED_PAD src0_sel:WORD_1
	v_cvt_pk_f16_f32 v91, v76, v77
	global_store_dword v[4:5], v90, off
	v_lshl_add_u64 v[4:5], v[2:3], 0, v[40:41]
	v_pk_fma_f32 v[72:73], v[98:99], v[76:77], v[72:73] op_sel_hi:[0,1,1]
	v_cvt_f32_f16_e32 v76, v107
	v_cvt_f32_f16_sdwa v77, v107 dst_sel:DWORD dst_unused:UNUSED_PAD src0_sel:WORD_1
	v_cvt_pk_f16_f32 v92, v72, v73
	global_store_dword v[4:5], v91, off
	v_lshl_add_u64 v[4:5], v[2:3], 0, v[42:43]
	v_pk_fma_f32 v[76:77], v[102:103], v[72:73], v[76:77] op_sel_hi:[0,1,1]
	v_cvt_f32_f16_e32 v72, v121
	v_cvt_f32_f16_sdwa v73, v121 dst_sel:DWORD dst_unused:UNUSED_PAD src0_sel:WORD_1
	v_cvt_pk_f16_f32 v93, v76, v77
	global_store_dword v[4:5], v92, off
	v_lshl_add_u64 v[4:5], v[2:3], 0, v[44:45]
	v_pk_fma_f32 v[72:73], v[104:105], v[76:77], v[72:73] op_sel_hi:[0,1,1]
	v_cvt_f32_f16_e32 v76, v117
	v_cvt_f32_f16_sdwa v77, v117 dst_sel:DWORD dst_unused:UNUSED_PAD src0_sel:WORD_1
	v_cvt_pk_f16_f32 v94, v72, v73
	global_store_dword v[4:5], v93, off
	v_lshl_add_u64 v[4:5], v[2:3], 0, v[46:47]
	v_pk_fma_f32 v[72:73], v[110:111], v[72:73], v[76:77] op_sel_hi:[0,1,1]
	v_cvt_f32_f16_e32 v76, v119
	v_cvt_f32_f16_sdwa v77, v119 dst_sel:DWORD dst_unused:UNUSED_PAD src0_sel:WORD_1
	v_cvt_pk_f16_f32 v95, v72, v73
	global_store_dword v[4:5], v94, off
	v_lshl_add_u64 v[4:5], v[2:3], 0, v[48:49]
	v_pk_fma_f32 v[76:77], v[114:115], v[72:73], v[76:77] op_sel_hi:[0,1,1]
	v_cvt_f32_f16_e32 v72, v123
	v_cvt_f32_f16_sdwa v73, v123 dst_sel:DWORD dst_unused:UNUSED_PAD src0_sel:WORD_1
	v_cvt_pk_f16_f32 v96, v76, v77
	global_store_dword v[4:5], v95, off
	v_lshl_add_u64 v[4:5], v[2:3], 0, v[50:51]
	v_pk_fma_f32 v[72:73], v[108:109], v[76:77], v[72:73] op_sel_hi:[0,1,1]
	v_cvt_f32_f16_e32 v76, v127
	v_cvt_f32_f16_sdwa v77, v127 dst_sel:DWORD dst_unused:UNUSED_PAD src0_sel:WORD_1
	v_cvt_pk_f16_f32 v97, v72, v73
	global_store_dword v[4:5], v96, off
	v_lshl_add_u64 v[4:5], v[2:3], 0, v[52:53]
	v_pk_fma_f32 v[76:77], v[118:119], v[72:73], v[76:77] op_sel_hi:[0,1,1]
	v_cvt_f32_f16_e32 v72, v126
	v_cvt_f32_f16_sdwa v73, v126 dst_sel:DWORD dst_unused:UNUSED_PAD src0_sel:WORD_1
	v_cvt_pk_f16_f32 v98, v76, v77
	global_store_dword v[4:5], v97, off
	v_lshl_add_u64 v[4:5], v[2:3], 0, v[54:55]
	v_pk_fma_f32 v[72:73], v[112:113], v[76:77], v[72:73] op_sel_hi:[0,1,1]
	v_cvt_f32_f16_e32 v76, v125
	v_cvt_f32_f16_sdwa v77, v125 dst_sel:DWORD dst_unused:UNUSED_PAD src0_sel:WORD_1
	v_cvt_pk_f16_f32 v99, v72, v73
	global_store_dword v[4:5], v98, off
	v_lshl_add_u64 v[4:5], v[2:3], 0, v[56:57]
	v_pk_fma_f32 v[72:73], v[116:117], v[72:73], v[76:77] op_sel_hi:[0,1,1]
	v_cvt_f32_f16_e32 v76, v128
	v_cvt_f32_f16_sdwa v77, v128 dst_sel:DWORD dst_unused:UNUSED_PAD src0_sel:WORD_1
	v_cvt_pk_f16_f32 v100, v72, v73
	global_store_dword v[4:5], v99, off
	v_lshl_add_u64 v[4:5], v[2:3], 0, v[58:59]
	v_pk_fma_f32 v[76:77], v[120:121], v[72:73], v[76:77] op_sel_hi:[0,1,1]
	v_cvt_f32_f16_e32 v72, v134
	v_cvt_f32_f16_sdwa v73, v134 dst_sel:DWORD dst_unused:UNUSED_PAD src0_sel:WORD_1
	v_cvt_pk_f16_f32 v101, v76, v77
	v_ashrrev_i32_e32 v67, 31, v66
	global_store_dword v[4:5], v100, off
	v_pk_fma_f32 v[72:73], v[122:123], v[76:77], v[72:73] op_sel_hi:[0,1,1]
	v_cvt_f32_f16_e32 v76, v129
	v_cvt_f32_f16_sdwa v77, v129 dst_sel:DWORD dst_unused:UNUSED_PAD src0_sel:WORD_1
	v_cvt_pk_f16_f32 v102, v72, v73
	v_lshl_add_u64 v[4:5], v[2:3], 0, v[60:61]
	v_lshlrev_b64 v[66:67], 13, v[66:67]
	v_pk_fma_f32 v[76:77], v[124:125], v[72:73], v[76:77] op_sel_hi:[0,1,1]
	v_cvt_f32_f16_e32 v72, v135
	v_cvt_f32_f16_sdwa v73, v135 dst_sel:DWORD dst_unused:UNUSED_PAD src0_sel:WORD_1
	global_store_dword v[4:5], v101, off
	v_lshl_add_u64 v[4:5], v[2:3], 0, v[74:75]
	global_store_dword v[4:5], v102, off
	s_waitcnt vmcnt(29)
	v_pk_fma_f32 v[68:69], v[68:69], v[76:77], v[72:73] op_sel_hi:[0,1,1]
	v_cvt_pk_f16_f32 v72, v76, v77
	v_cvt_pk_f16_f32 v68, v68, v69
	v_lshl_add_u64 v[4:5], v[2:3], 0, v[64:65]
	v_lshl_add_u64 v[2:3], v[2:3], 0, v[66:67]
	global_store_dword v[4:5], v72, off
	global_store_dword v[2:3], v68, off

; __global__ void __launch_bounds__(512, 2) hybrid_fwd(Args args) {
;     extern __shared__ __attribute__((aligned(16))) unsigned char lds_raw[];
	.amdhsa_kernel _Z10hybrid_fwd4Args
		.amdhsa_group_segment_fixed_size 0
		.amdhsa_private_segment_fixed_size 0
		.amdhsa_kernarg_size 576
		.amdhsa_user_sgpr_count 2
		.amdhsa_user_sgpr_dispatch_ptr 0
		.amdhsa_user_sgpr_queue_ptr 0
		.amdhsa_user_sgpr_kernarg_segment_ptr 1
		.amdhsa_user_sgpr_dispatch_id 0
		.amdhsa_user_sgpr_kernarg_preload_length 0
		.amdhsa_user_sgpr_kernarg_preload_offset 0
		.amdhsa_user_sgpr_private_segment_size 0
		.amdhsa_uses_dynamic_stack 0
		.amdhsa_enable_private_segment 0
		.amdhsa_system_sgpr_workgroup_id_x 1
		.amdhsa_system_sgpr_workgroup_id_y 0
		.amdhsa_system_sgpr_workgroup_id_z 0
		.amdhsa_system_sgpr_workgroup_info 0
		.amdhsa_system_vgpr_workitem_id 0
		.amdhsa_next_free_vgpr 256
		.amdhsa_next_free_sgpr 102
		.amdhsa_accum_offset 256
		.amdhsa_reserve_vcc 1
		.amdhsa_float_round_mode_32 0
		.amdhsa_float_round_mode_16_64 0
		.amdhsa_float_denorm_mode_32 3
		.amdhsa_float_denorm_mode_16_64 3
		.amdhsa_dx10_clamp 1
		.amdhsa_ieee_mode 1
		.amdhsa_fp16_overflow 0
		.amdhsa_tg_split 0
		.amdhsa_exception_fp_ieee_invalid_op 0
		.amdhsa_exception_fp_denorm_src 0
		.amdhsa_exception_fp_ieee_div_zero 0
		.amdhsa_exception_fp_ieee_overflow 0
		.amdhsa_exception_fp_ieee_underflow 0
		.amdhsa_exception_fp_ieee_inexact 0
		.amdhsa_exception_int_div_zero 0
	.end_amdhsa_kernel

; __global__ void __launch_bounds__(512, 2) hybrid_fwd(Args args) {
;     extern __shared__ __attribute__((aligned(16))) unsigned char lds_raw[];
amdhsa.kernels:
  - .agpr_count:     0
    .args:
      - .offset:         0
        .size:           320
        .value_kind:     by_value
      - .offset:         320
        .size:           4
        .value_kind:     hidden_block_count_x
      - .offset:         324
        .size:           4
        .value_kind:     hidden_block_count_y
      - .offset:         328
        .size:           4
        .value_kind:     hidden_block_count_z
      - .offset:         332
        .size:           2
        .value_kind:     hidden_group_size_x
      - .offset:         334
        .size:           2
        .value_kind:     hidden_group_size_y
      - .offset:         336
        .size:           2
        .value_kind:     hidden_group_size_z
      - .offset:         338
        .size:           2
        .value_kind:     hidden_remainder_x
      - .offset:         340
        .size:           2
        .value_kind:     hidden_remainder_y
      - .offset:         342
        .size:           2
        .value_kind:     hidden_remainder_z
      - .offset:         360
        .size:           8
        .value_kind:     hidden_global_offset_x
      - .offset:         368
        .size:           8
        .value_kind:     hidden_global_offset_y
      - .offset:         376
        .size:           8
        .value_kind:     hidden_global_offset_z
      - .offset:         384
        .size:           2
        .value_kind:     hidden_grid_dims
      - .offset:         440
        .size:           4
        .value_kind:     hidden_dynamic_lds_size
    .group_segment_fixed_size: 0
    .kernarg_segment_align: 8
    .kernarg_segment_size: 576
    .language:       OpenCL C
    .language_version:
      - 2
      - 0
    .max_flat_workgroup_size: 512
    .name:           _Z10hybrid_fwd4Args
    .private_segment_fixed_size: 0
    .sgpr_count:     108
    .sgpr_spill_count: 121
    .symbol:         _Z10hybrid_fwd4Args.kd
    .uniform_work_group_size: 1
    .uses_dynamic_stack: false
    .vgpr_count:     256
    .vgpr_spill_count: 0
    .wavefront_size: 64
